# NA attention tile loop: staged K/V tile is written to LDS at the top of the next iteration and tile t+2 is fetched right after (one whole iteration of load latency cover)
# speedup vs baseline: 1.0435x; 1.0025x over previous
.LBB0_2290:
	s_or_b64 exec, exec, s[50:51]
	v_mov_b32_e32 v15, 0
	s_cmp_gt_i32 s89, -16
	v_mov_b32_e32 v14, v15
	v_mov_b32_e32 v13, v15
	v_mov_b32_e32 v12, v15
	v_mov_b32_e32 v11, v15
	v_mov_b32_e32 v10, v15
	v_mov_b32_e32 v9, v15
	v_mov_b32_e32 v8, v15
	v_mov_b32_e32 v7, v15
	v_mov_b32_e32 v6, v15
	v_mov_b32_e32 v5, v15
	v_mov_b32_e32 v4, v15
	v_mov_b32_e32 v3, v15
	v_mov_b32_e32 v2, v15
	v_mov_b32_e32 v1, v15
	v_mov_b32_e32 v0, v15
	v_mov_b32_e32 v31, v15
	v_mov_b32_e32 v30, v15
	v_mov_b32_e32 v29, v15
	v_mov_b32_e32 v28, v15
	v_mov_b32_e32 v27, v15
	v_mov_b32_e32 v26, v15
	v_mov_b32_e32 v25, v15
	v_mov_b32_e32 v24, v15
	v_mov_b32_e32 v23, v15
	v_mov_b32_e32 v22, v15
	v_mov_b32_e32 v21, v15
	v_mov_b32_e32 v20, v15
	v_mov_b32_e32 v19, v15
	v_mov_b32_e32 v18, v15
	v_mov_b32_e32 v17, v15
	v_mov_b32_e32 v16, v15
	v_mov_b32_e32 v113, v15
	s_waitcnt lgkmcnt(0)
	s_barrier
	s_cbranch_scc0 .LBB0_2272
	s_max_u32 s4, s87, 4
	s_min_u32 s5, s63, 0xf8
	s_sub_i32 s5, s4, s5
	s_lshl_b32 s5, s5, 6
	s_add_i32 s63, s5, 0xfffffd40
	s_mul_i32 s5, s4, 0x7c
	s_mulk_i32 s86, 0x1f0
	s_add_i32 s80, s4, -4
	s_sub_i32 s5, s5, s86
	s_cmp_lg_u32 s88, 0
	s_cselect_b64 s[50:51], -1, 0
	s_add_i32 s81, s89, 11
	s_add_i32 s86, s89, 15
	v_mov_b32_e32 v85, v77
	s_cmp_lg_u64 s[50:51], 0
	v_max_i32_e32 v0, 4, v35
	v_max_i32_e32 v2, 3, v34
	v_lshl_add_u64 v[92:93], v[32:33], 0, v[84:85]
	v_add_u32_e32 v85, s5, v138
	s_subb_u32 s5, s87, 0
	v_add_u32_e32 v0, -4, v0
	v_max_i32_e32 v1, 4, v34
	v_add_u32_e32 v2, -3, v2
	s_min_u32 s5, s5, 0xf8
	v_add_u32_e32 v1, -4, v1
	v_min_u32_e32 v2, 0xf8, v2
	v_min_u32_e32 v142, 0xf8, v0
	s_sub_i32 s87, s5, s4
	v_mov_b32_e32 v76, 0
	v_min_u32_e32 v141, 0xf8, v1
	s_mov_b32 s76, 0
	v_add_u32_e32 v143, 7, v2
	v_add_u32_e32 v144, 8, v142
	s_add_i32 s87, s87, 16
	v_mov_b32_e32 v112, 0xff800000
	v_mov_b32_e32 v38, 0
	v_mov_b32_e32 v39, v76
	v_mov_b32_e32 v42, 0
	v_mov_b32_e32 v43, v76
	v_mov_b32_e32 v46, 0
	v_mov_b32_e32 v47, v76
	v_mov_b32_e32 v96, 0
	v_mov_b32_e32 v97, v76
	v_mov_b32_e32 v100, 0
	v_mov_b32_e32 v101, v76
	v_mov_b32_e32 v102, 0
	v_mov_b32_e32 v103, v76
	v_mov_b32_e32 v104, 0
	v_mov_b32_e32 v105, v76
	v_mov_b32_e32 v106, 0
	v_mov_b32_e32 v107, v76
	v_mov_b32_e32 v108, 0
	v_mov_b32_e32 v109, v76
	v_mov_b32_e32 v110, 0
	v_mov_b32_e32 v111, v76
	v_mov_b32_e32 v34, 0
	v_mov_b32_e32 v35, v76
	v_mov_b32_e32 v36, 0
	v_mov_b32_e32 v37, v76
	v_mov_b32_e32 v40, 0
	v_mov_b32_e32 v41, v76
	v_mov_b32_e32 v44, 0
	v_mov_b32_e32 v45, v76
	v_mov_b32_e32 v94, 0
	v_mov_b32_e32 v95, v76
	v_mov_b32_e32 v98, 0
	v_mov_b32_e32 v99, v76
	v_add_u32_e32 v0, 1, v87
	v_lshlrev_b32_e32 v0, 6, v0
	v_add_u32_e32 v0, 0x100, v0
	v_ashrrev_i32_e32 v1, 31, v0
	v_lshl_add_u64 v[2:3], v[90:91], 0, v[0:1]
	v_lshlrev_b64 v[2:3], 7, v[2:3]
	v_lshl_add_u64 v[2:3], v[82:83], 0, v[2:3]
	v_lshl_add_u64 v[0:1], v[0:1], 1, v[92:93]
	global_load_dwordx4 v[64:67], v[2:3], off
	global_load_dwordx4 v[68:71], v[0:1], off
.LBB0_2292:
	s_add_i32 s88, s76, 1
	s_cmp_lt_i32 s76, s86
	s_cselect_b64 s[74:75], -1, 0
	s_cbranch_scc0 .Lna_no_store
	s_and_b32 s4, s76, 1
	s_xor_b32 s4, s4, 1
	s_mulk_i32 s4, 0x2400
	v_add_u32_e32 v236, s4, v75
	s_waitcnt vmcnt(1)
	ds_write_b128 v236, v[64:67]
	s_waitcnt vmcnt(0)
	ds_write_b128 v236, v[68:71] offset:18432
.Lna_no_store:
	s_add_i32 s4, s86, -1
	s_add_i32 s98, s63, 64
	s_add_i32 s99, s81, -1
	s_cmp_ge_i32 s76, s4
	s_cbranch_scc1 .LBB0_2296
	v_mov_b32_e32 v0, s98
	s_cmp_ge_i32 s76, s99
	s_cbranch_scc1 .LBB0_2295
	s_add_i32 s4, s88, 1
	v_add_u32_e32 v0, s4, v87
	v_lshlrev_b32_e32 v0, 6, v0
	v_add_u32_e32 v0, 0x100, v0

.LBB0_2298:
.LBB0_2299:
.LBB0_2300:
	s_add_i32 s63, s63, 64
	s_cmp_eq_u32 s87, s88
	v_add_u32_e32 v85, 0x7c, v85
	s_waitcnt lgkmcnt(0)
	s_barrier
	s_cbranch_scc1 .LBB0_2272
	v_mov_b32_e32 v76, v113
	v_mov_b32_e32 v112, v145
	s_mov_b32 s76, s88
	v_mov_b32_e32 v38, v16
	v_mov_b32_e32 v39, v17
	v_mov_b32_e32 v42, v18
	v_mov_b32_e32 v43, v19
	v_mov_b32_e32 v46, v20
	v_mov_b32_e32 v47, v21
	v_mov_b32_e32 v96, v22
	v_mov_b32_e32 v97, v23
	v_mov_b32_e32 v100, v24
	v_mov_b32_e32 v101, v25
	v_mov_b32_e32 v102, v26
	v_mov_b32_e32 v103, v27
	v_mov_b32_e32 v104, v28
	v_mov_b32_e32 v105, v29
	v_mov_b32_e32 v106, v30
	v_mov_b32_e32 v107, v31
	v_mov_b32_e32 v108, v0
	v_mov_b32_e32 v109, v1
	v_mov_b32_e32 v110, v2
	v_mov_b32_e32 v111, v3
	v_mov_b32_e32 v34, v4
	v_mov_b32_e32 v35, v5
	v_mov_b32_e32 v36, v6
	v_mov_b32_e32 v37, v7
	v_mov_b32_e32 v40, v8
	v_mov_b32_e32 v41, v9
	v_mov_b32_e32 v44, v10
	v_mov_b32_e32 v45, v11
	v_mov_b32_e32 v94, v12
	v_mov_b32_e32 v95, v13
	v_mov_b32_e32 v98, v14
	v_mov_b32_e32 v99, v15
	s_branch .LBB0_2292
